# attention softmax slot: transcendental ops alternate with independent plain VALU ops (pair sums and bf16 packing of the first half ride beside the second half's exp)
# baseline (speedup 1.0000x reference)
.Latt2_h0p0_xend:
	s_barrier
	s_cmp_gt_i32 s49, s48
	s_cbranch_scc1 .Latt2_yskip_h0p0
	s_bitcmp1_b32 s49, 0
	s_cselect_b32 s53, 0x5900, 0
	v_add_u32_e32 v1, s53, v193
	s_waitcnt lgkmcnt(0)
	s_nop 3
	v_fma_f32 v64, v64, v230, -v165
	v_fma_f32 v65, v65, v231, -v165
	v_fma_f32 v66, v66, v232, -v165
	v_fma_f32 v67, v67, v233, -v165
	ds_read_b128 v[230:233], v1 offset:22736
	v_fma_f32 v68, v68, v234, -v165
	v_fma_f32 v69, v69, v235, -v165
	v_fma_f32 v70, v70, v236, -v165
	v_fma_f32 v71, v71, v237, -v165
	v_fma_f32 v72, v72, v238, -v165
	v_fma_f32 v73, v73, v239, -v165
	v_fma_f32 v74, v74, v240, -v165
	v_fma_f32 v75, v75, v241, -v165
	v_fma_f32 v76, v76, v242, -v165
	v_fma_f32 v77, v77, v243, -v165
	v_fma_f32 v78, v78, v244, -v165
	v_fma_f32 v79, v79, v245, -v165
	v_exp_f32_e32 v64, v64
	v_fma_f32 v48, v48, v246, -v165
	v_exp_f32_e32 v65, v65
	v_fma_f32 v49, v49, v247, -v165
	v_exp_f32_e32 v66, v66
	v_fma_f32 v50, v50, v248, -v165
	v_exp_f32_e32 v67, v67
	v_fma_f32 v51, v51, v249, -v165
	v_exp_f32_e32 v68, v68
	v_fma_f32 v52, v52, v250, -v165
	v_exp_f32_e32 v69, v69
	v_fma_f32 v53, v53, v251, -v165
	v_exp_f32_e32 v70, v70
	v_fma_f32 v54, v54, v252, -v165
	v_exp_f32_e32 v71, v71
	v_fma_f32 v55, v55, v253, -v165
	v_exp_f32_e32 v72, v72
	v_fma_f32 v56, v56, v214, -v165
	v_exp_f32_e32 v73, v73
	v_fma_f32 v57, v57, v215, -v165
	v_exp_f32_e32 v74, v74
	v_fma_f32 v58, v58, v216, -v165
	v_exp_f32_e32 v75, v75
	v_fma_f32 v59, v59, v217, -v165
	s_waitcnt lgkmcnt(0)
	v_exp_f32_e32 v76, v76
	v_fma_f32 v60, v60, v230, -v165
	v_exp_f32_e32 v77, v77
	v_fma_f32 v61, v61, v231, -v165
	v_exp_f32_e32 v78, v78
	v_fma_f32 v62, v62, v232, -v165
	v_exp_f32_e32 v79, v79
	v_fma_f32 v63, v63, v233, -v165
	v_exp_f32_e32 v48, v48
	v_add_f32_e32 v234, v64, v65
	v_exp_f32_e32 v49, v49
	v_add_f32_e32 v235, v66, v67
	v_exp_f32_e32 v50, v50
	v_add_f32_e32 v236, v68, v69
	v_exp_f32_e32 v51, v51
	v_add_f32_e32 v237, v70, v71
	v_exp_f32_e32 v52, v52
	v_add_f32_e32 v238, v72, v73
	v_exp_f32_e32 v53, v53
	v_add_f32_e32 v239, v74, v75
	v_exp_f32_e32 v54, v54
	v_add_f32_e32 v240, v76, v77
	v_exp_f32_e32 v55, v55
	v_add_f32_e32 v241, v78, v79
	v_exp_f32_e32 v56, v56
	v_cvt_pk_bf16_f32 v64, v64, v65
	v_exp_f32_e32 v57, v57
	v_cvt_pk_bf16_f32 v65, v66, v67
	v_exp_f32_e32 v58, v58
	v_cvt_pk_bf16_f32 v66, v68, v69
	v_exp_f32_e32 v59, v59
	v_cvt_pk_bf16_f32 v67, v70, v71
	v_exp_f32_e32 v60, v60
	v_cvt_pk_bf16_f32 v68, v72, v73
	v_exp_f32_e32 v61, v61
	v_cvt_pk_bf16_f32 v69, v74, v75
	v_exp_f32_e32 v62, v62
	v_cvt_pk_bf16_f32 v70, v76, v77
	v_exp_f32_e32 v63, v63
	v_cvt_pk_bf16_f32 v71, v78, v79
	v_add_f32_e32 v242, v48, v49
	v_add_f32_e32 v243, v50, v51
	v_add_f32_e32 v244, v52, v53
	v_add_f32_e32 v245, v54, v55
	v_add_f32_e32 v246, v56, v57
	v_add_f32_e32 v247, v58, v59
	v_add_f32_e32 v248, v60, v61
	v_add_f32_e32 v249, v62, v63
	v_cvt_pk_bf16_f32 v48, v48, v49
	v_cvt_pk_bf16_f32 v49, v50, v51
	v_cvt_pk_bf16_f32 v50, v52, v53
	v_cvt_pk_bf16_f32 v51, v54, v55
	v_cvt_pk_bf16_f32 v52, v56, v57
	v_cvt_pk_bf16_f32 v53, v58, v59
	v_cvt_pk_bf16_f32 v54, v60, v61
	v_cvt_pk_bf16_f32 v55, v62, v63
	v_add_f32_e32 v234, v234, v235
	v_add_f32_e32 v236, v236, v237
	v_add_f32_e32 v238, v238, v239
	v_add_f32_e32 v240, v240, v241
	v_add_f32_e32 v242, v242, v243
	v_add_f32_e32 v244, v244, v245
	v_add_f32_e32 v246, v246, v247
	v_add_f32_e32 v248, v248, v249
	v_add_f32_e32 v234, v234, v236
	v_add_f32_e32 v238, v238, v240
	v_add_f32_e32 v242, v242, v244
	v_add_f32_e32 v246, v246, v248
	v_add_f32_e32 v234, v234, v238
	v_add_f32_e32 v242, v242, v246
	v_add_f32_e32 v234, v234, v242
	v_add_f32_e32 v151, v151, v234

.Latt2_h1p0_xend:
	s_waitcnt lgkmcnt(0)
	s_barrier
	s_cmp_gt_i32 s49, s48
	s_cbranch_scc1 .Latt2_yskip_h1p0
	s_bitcmp1_b32 s49, 0
	s_cselect_b32 s53, 0x5900, 0
	v_add_u32_e32 v1, s53, v193
	s_waitcnt lgkmcnt(0)
	s_nop 3
	v_fma_f32 v64, v64, v230, -v165
	v_fma_f32 v65, v65, v231, -v165
	v_fma_f32 v66, v66, v232, -v165
	v_fma_f32 v67, v67, v233, -v165
	ds_read_b128 v[230:233], v1 offset:22736
	v_fma_f32 v68, v68, v234, -v165
	v_fma_f32 v69, v69, v235, -v165
	v_fma_f32 v70, v70, v236, -v165
	v_fma_f32 v71, v71, v237, -v165
	v_fma_f32 v72, v72, v238, -v165
	v_fma_f32 v73, v73, v239, -v165
	v_fma_f32 v74, v74, v240, -v165
	v_fma_f32 v75, v75, v241, -v165
	v_fma_f32 v76, v76, v242, -v165
	v_fma_f32 v77, v77, v243, -v165
	v_fma_f32 v78, v78, v244, -v165
	v_fma_f32 v79, v79, v245, -v165
	v_exp_f32_e32 v64, v64
	v_fma_f32 v48, v48, v246, -v165
	v_exp_f32_e32 v65, v65
	v_fma_f32 v49, v49, v247, -v165
	v_exp_f32_e32 v66, v66
	v_fma_f32 v50, v50, v248, -v165
	v_exp_f32_e32 v67, v67
	v_fma_f32 v51, v51, v249, -v165
	v_exp_f32_e32 v68, v68
	v_fma_f32 v52, v52, v250, -v165
	v_exp_f32_e32 v69, v69
	v_fma_f32 v53, v53, v251, -v165
	v_exp_f32_e32 v70, v70
	v_fma_f32 v54, v54, v252, -v165
	v_exp_f32_e32 v71, v71
	v_fma_f32 v55, v55, v253, -v165
	v_exp_f32_e32 v72, v72
	v_fma_f32 v56, v56, v214, -v165
	v_exp_f32_e32 v73, v73
	v_fma_f32 v57, v57, v215, -v165
	v_exp_f32_e32 v74, v74
	v_fma_f32 v58, v58, v216, -v165
	v_exp_f32_e32 v75, v75
	v_fma_f32 v59, v59, v217, -v165
	s_waitcnt lgkmcnt(0)
	v_exp_f32_e32 v76, v76
	v_fma_f32 v60, v60, v230, -v165
	v_exp_f32_e32 v77, v77
	v_fma_f32 v61, v61, v231, -v165
	v_exp_f32_e32 v78, v78
	v_fma_f32 v62, v62, v232, -v165
	v_exp_f32_e32 v79, v79
	v_fma_f32 v63, v63, v233, -v165
	v_exp_f32_e32 v48, v48
	v_add_f32_e32 v234, v64, v65
	v_exp_f32_e32 v49, v49
	v_add_f32_e32 v235, v66, v67
	v_exp_f32_e32 v50, v50
	v_add_f32_e32 v236, v68, v69
	v_exp_f32_e32 v51, v51
	v_add_f32_e32 v237, v70, v71
	v_exp_f32_e32 v52, v52
	v_add_f32_e32 v238, v72, v73
	v_exp_f32_e32 v53, v53
	v_add_f32_e32 v239, v74, v75
	v_exp_f32_e32 v54, v54
	v_add_f32_e32 v240, v76, v77
	v_exp_f32_e32 v55, v55
	v_add_f32_e32 v241, v78, v79
	v_exp_f32_e32 v56, v56
	v_cvt_pk_bf16_f32 v64, v64, v65
	v_exp_f32_e32 v57, v57
	v_cvt_pk_bf16_f32 v65, v66, v67
	v_exp_f32_e32 v58, v58
	v_cvt_pk_bf16_f32 v66, v68, v69
	v_exp_f32_e32 v59, v59
	v_cvt_pk_bf16_f32 v67, v70, v71
	v_exp_f32_e32 v60, v60
	v_cvt_pk_bf16_f32 v68, v72, v73
	v_exp_f32_e32 v61, v61
	v_cvt_pk_bf16_f32 v69, v74, v75
	v_exp_f32_e32 v62, v62
	v_cvt_pk_bf16_f32 v70, v76, v77
	v_exp_f32_e32 v63, v63
	v_cvt_pk_bf16_f32 v71, v78, v79
	v_add_f32_e32 v242, v48, v49
	v_add_f32_e32 v243, v50, v51
	v_add_f32_e32 v244, v52, v53
	v_add_f32_e32 v245, v54, v55
	v_add_f32_e32 v246, v56, v57
	v_add_f32_e32 v247, v58, v59
	v_add_f32_e32 v248, v60, v61
	v_add_f32_e32 v249, v62, v63
	v_cvt_pk_bf16_f32 v48, v48, v49
	v_cvt_pk_bf16_f32 v49, v50, v51
	v_cvt_pk_bf16_f32 v50, v52, v53
	v_cvt_pk_bf16_f32 v51, v54, v55
	v_cvt_pk_bf16_f32 v52, v56, v57
	v_cvt_pk_bf16_f32 v53, v58, v59
	v_cvt_pk_bf16_f32 v54, v60, v61
	v_cvt_pk_bf16_f32 v55, v62, v63
	v_add_f32_e32 v234, v234, v235
	v_add_f32_e32 v236, v236, v237
	v_add_f32_e32 v238, v238, v239
	v_add_f32_e32 v240, v240, v241
	v_add_f32_e32 v242, v242, v243
	v_add_f32_e32 v244, v244, v245
	v_add_f32_e32 v246, v246, v247
	v_add_f32_e32 v248, v248, v249
	v_add_f32_e32 v234, v234, v236
	v_add_f32_e32 v238, v238, v240
	v_add_f32_e32 v242, v242, v244
	v_add_f32_e32 v246, v246, v248
	v_add_f32_e32 v234, v234, v238
	v_add_f32_e32 v242, v242, v246
	v_add_f32_e32 v234, v234, v242
	v_add_f32_e32 v151, v151, v234
